# P4 epilogue data path rewritten with packed f32 multiplies in place (max, square, times row factor, bf16 pack); 132 fewer VALU instructions per tile
# speedup vs baseline: 1.0098x; 1.0054x over previous
; __device__ __forceinline__ unsigned cvt_pk_bf16(float lo, float hi) { unsigned r; asm volatile("v_cvt_pk_bf16_f32 %0, %1, %2" : "=v"(r) : "v"(lo), "v"(hi)); return r; }
;     __device__ __forceinline__ void operator()(const f32x4 (&acc)[2][2][4][2], const Unit& u, int wr, int wc, int fr, int fq) const {
;     ...
;         for (int ai = 0; ai < 2; ++ai)
; #pragma unroll
;             for (int m = 0; m < 4; ++m) { const int row = row0 + ai * HALF + m * 16; const float rr = r2[ai][m];
;                 bf16_t* rowp = O + ((size_t)u.pm * (ldc / 64) * 256 + (size_t)(row - u.pm * BM)) * 64 + (size_t)(col0 >> 6) * (256 * 64) + (col0 & 63);
; #pragma unroll
;                 for (int bj = 0; bj < 2; ++bj) { f32x4 v0 = acc[ai][bj][m][0], v1 = acc[ai][bj][m][1];
; #pragma unroll
;                     for (int e = 0; e < 4; ++e) { const float a = fmaxf(v0[e], 0.f), b = fmaxf(v1[e], 0.f); v0[e] = a * a * rr; v1[e] = b * b * rr; }
;                     u32x4 w; w.x = cvt_pk_bf16(v0[0], v0[1]); w.y = cvt_pk_bf16(v0[2], v0[3]); w.z = cvt_pk_bf16(v1[0], v1[1]); w.w = cvt_pk_bf16(v1[2], v1[3]);
;                     *(u32x4*)(rowp + (size_t)bj * (2 * 256 * 64)) = w; } }
.Lp4_r2_cached:
	v_max_f32_e32 v124, 0, v124
	v_max_f32_e32 v125, 0, v125
	v_max_f32_e32 v126, 0, v126
	v_max_f32_e32 v127, 0, v127
	v_max_f32_e32 v120, 0, v120
	v_max_f32_e32 v121, 0, v121
	v_max_f32_e32 v122, 0, v122
	v_max_f32_e32 v123, 0, v123
	v_pk_mul_f32 v[124:125], v[124:125], v[124:125]
	v_pk_mul_f32 v[126:127], v[126:127], v[126:127]
	v_pk_mul_f32 v[120:121], v[120:121], v[120:121]
	v_pk_mul_f32 v[122:123], v[122:123], v[122:123]
	v_pk_mul_f32 v[124:125], v[124:125], v[244:245] op_sel:[0,1] op_sel_hi:[1,1]
	v_pk_mul_f32 v[126:127], v[126:127], v[244:245] op_sel:[0,1] op_sel_hi:[1,1]
	v_pk_mul_f32 v[120:121], v[120:121], v[244:245] op_sel:[0,1] op_sel_hi:[1,1]
	v_pk_mul_f32 v[122:123], v[122:123], v[244:245] op_sel:[0,1] op_sel_hi:[1,1]
	v_cvt_pk_bf16_f32 v123, v122, v123
	v_cvt_pk_bf16_f32 v122, v120, v121
	v_cvt_pk_bf16_f32 v120, v124, v125
	v_cvt_pk_bf16_f32 v121, v126, v127
	s_lshl_b32 s2, s6, 8
	s_or_b32 s21, s2, s54
	s_ashr_i32 s31, s30, 31
	s_lshl_b64 s[8:9], s[30:31], 21
	s_ashr_i32 s6, s21, 6
	s_ashr_i32 s7, s6, 31
	s_lshl_b64 s[6:7], s[6:7], 15
	s_add_u32 s8, s42, s8
	s_addc_u32 s9, s43, s9
	v_lshl_add_u64 v[130:131], s[8:9], 0, v[144:145]
	v_lshl_add_u64 v[130:131], v[130:131], 0, s[6:7]
	v_lshl_add_u64 v[130:131], v[130:131], 0, v[140:141]
	global_store_dwordx4 v[130:131], v[120:123], off
	v_max_f32_e32 v116, 0, v116
	v_max_f32_e32 v117, 0, v117
	v_max_f32_e32 v118, 0, v118
	v_max_f32_e32 v119, 0, v119
	v_max_f32_e32 v112, 0, v112
	v_max_f32_e32 v113, 0, v113
	v_max_f32_e32 v114, 0, v114
	v_max_f32_e32 v115, 0, v115
	v_pk_mul_f32 v[116:117], v[116:117], v[116:117]
	v_pk_mul_f32 v[118:119], v[118:119], v[118:119]
	v_pk_mul_f32 v[112:113], v[112:113], v[112:113]
	v_pk_mul_f32 v[114:115], v[114:115], v[114:115]
	v_pk_mul_f32 v[116:117], v[116:117], v[244:245] op_sel:[0,1] op_sel_hi:[1,1]
	v_pk_mul_f32 v[118:119], v[118:119], v[244:245] op_sel:[0,1] op_sel_hi:[1,1]
	v_pk_mul_f32 v[112:113], v[112:113], v[244:245] op_sel:[0,1] op_sel_hi:[1,1]
	v_pk_mul_f32 v[114:115], v[114:115], v[244:245] op_sel:[0,1] op_sel_hi:[1,1]
	v_cvt_pk_bf16_f32 v115, v114, v115
	v_cvt_pk_bf16_f32 v114, v112, v113
	v_cvt_pk_bf16_f32 v112, v116, v117
	v_cvt_pk_bf16_f32 v113, v118, v119
	v_add_co_u32_e32 v116, vcc, s49, v130
	s_nop 1
	v_addc_co_u32_e32 v117, vcc, 0, v131, vcc
	global_store_dwordx4 v[116:117], v[112:115], off
	v_max_f32_e32 v108, 0, v108
	v_max_f32_e32 v109, 0, v109
	v_max_f32_e32 v110, 0, v110
	v_max_f32_e32 v111, 0, v111
	v_max_f32_e32 v104, 0, v104
	v_max_f32_e32 v105, 0, v105
	v_max_f32_e32 v106, 0, v106
	v_max_f32_e32 v107, 0, v107
	v_pk_mul_f32 v[108:109], v[108:109], v[108:109]
	v_pk_mul_f32 v[110:111], v[110:111], v[110:111]
	v_pk_mul_f32 v[104:105], v[104:105], v[104:105]
	v_pk_mul_f32 v[106:107], v[106:107], v[106:107]
	v_pk_mul_f32 v[108:109], v[108:109], v[246:247] op_sel_hi:[1,0]
	v_pk_mul_f32 v[110:111], v[110:111], v[246:247] op_sel_hi:[1,0]
	v_pk_mul_f32 v[104:105], v[104:105], v[246:247] op_sel_hi:[1,0]
	v_pk_mul_f32 v[106:107], v[106:107], v[246:247] op_sel_hi:[1,0]
	v_cvt_pk_bf16_f32 v107, v106, v107
	v_cvt_pk_bf16_f32 v106, v104, v105
	v_cvt_pk_bf16_f32 v104, v108, v109
	v_cvt_pk_bf16_f32 v105, v110, v111
	v_lshl_add_u64 v[112:113], s[8:9], 0, v[146:147]
	v_lshl_add_u64 v[112:113], v[112:113], 0, s[6:7]
	v_lshl_add_u64 v[112:113], v[112:113], 0, v[140:141]
	global_store_dwordx4 v[112:113], v[104:107], off
	v_max_f32_e32 v100, 0, v100
	v_max_f32_e32 v101, 0, v101
	v_max_f32_e32 v102, 0, v102
	v_max_f32_e32 v103, 0, v103
	v_max_f32_e32 v96, 0, v96
	v_max_f32_e32 v97, 0, v97
	v_max_f32_e32 v98, 0, v98
	v_max_f32_e32 v99, 0, v99
	v_pk_mul_f32 v[100:101], v[100:101], v[100:101]
	v_pk_mul_f32 v[102:103], v[102:103], v[102:103]
	v_pk_mul_f32 v[96:97], v[96:97], v[96:97]
	v_pk_mul_f32 v[98:99], v[98:99], v[98:99]
	v_pk_mul_f32 v[100:101], v[100:101], v[246:247] op_sel_hi:[1,0]
	v_pk_mul_f32 v[102:103], v[102:103], v[246:247] op_sel_hi:[1,0]
	v_pk_mul_f32 v[96:97], v[96:97], v[246:247] op_sel_hi:[1,0]
	v_pk_mul_f32 v[98:99], v[98:99], v[246:247] op_sel_hi:[1,0]
	v_cvt_pk_bf16_f32 v99, v98, v99
	v_cvt_pk_bf16_f32 v98, v96, v97
	v_cvt_pk_bf16_f32 v96, v100, v101
	v_cvt_pk_bf16_f32 v97, v102, v103
	v_add_co_u32_e32 v100, vcc, s49, v112
	s_nop 1
	v_addc_co_u32_e32 v101, vcc, 0, v113, vcc
	global_store_dwordx4 v[100:101], v[96:99], off
	v_max_f32_e32 v92, 0, v92
	v_max_f32_e32 v93, 0, v93
	v_max_f32_e32 v94, 0, v94
	v_max_f32_e32 v95, 0, v95
	v_max_f32_e32 v88, 0, v88
	v_max_f32_e32 v89, 0, v89
	v_max_f32_e32 v90, 0, v90
	v_max_f32_e32 v91, 0, v91
	v_pk_mul_f32 v[92:93], v[92:93], v[92:93]
	v_pk_mul_f32 v[94:95], v[94:95], v[94:95]
	v_pk_mul_f32 v[88:89], v[88:89], v[88:89]
	v_pk_mul_f32 v[90:91], v[90:91], v[90:91]
	v_pk_mul_f32 v[92:93], v[92:93], v[246:247] op_sel:[0,1] op_sel_hi:[1,1]
	v_pk_mul_f32 v[94:95], v[94:95], v[246:247] op_sel:[0,1] op_sel_hi:[1,1]
	v_pk_mul_f32 v[88:89], v[88:89], v[246:247] op_sel:[0,1] op_sel_hi:[1,1]
	v_pk_mul_f32 v[90:91], v[90:91], v[246:247] op_sel:[0,1] op_sel_hi:[1,1]
	v_cvt_pk_bf16_f32 v91, v90, v91
	v_cvt_pk_bf16_f32 v90, v88, v89
	v_cvt_pk_bf16_f32 v88, v92, v93
	v_cvt_pk_bf16_f32 v89, v94, v95
	v_lshl_add_u64 v[96:97], s[8:9], 0, v[148:149]
	v_lshl_add_u64 v[96:97], v[96:97], 0, s[6:7]
	v_lshl_add_u64 v[96:97], v[96:97], 0, v[140:141]
	global_store_dwordx4 v[96:97], v[88:91], off
	v_max_f32_e32 v84, 0, v84
	v_max_f32_e32 v85, 0, v85
	v_max_f32_e32 v86, 0, v86
	v_max_f32_e32 v87, 0, v87
	v_max_f32_e32 v80, 0, v80
	v_max_f32_e32 v81, 0, v81
	v_max_f32_e32 v82, 0, v82
	v_max_f32_e32 v83, 0, v83
	v_pk_mul_f32 v[84:85], v[84:85], v[84:85]
	v_pk_mul_f32 v[86:87], v[86:87], v[86:87]
; __device__ __forceinline__ unsigned cvt_pk_bf16(float lo, float hi) { unsigned r; asm volatile("v_cvt_pk_bf16_f32 %0, %1, %2" : "=v"(r) : "v"(lo), "v"(hi)); return r; }
;     __device__ __forceinline__ void operator()(const f32x4 (&acc)[2][2][4][2], const Unit& u, int wr, int wc, int fr, int fq) const {
;     ...
;             for (int m = 0; m < 4; ++m) { const int row = row0 + ai * HALF + m * 16; const float rr = r2[ai][m];
;                 bf16_t* rowp = O + ((size_t)u.pm * (ldc / 64) * 256 + (size_t)(row - u.pm * BM)) * 64 + (size_t)(col0 >> 6) * (256 * 64) + (col0 & 63);
; #pragma unroll
;                 for (int bj = 0; bj < 2; ++bj) { f32x4 v0 = acc[ai][bj][m][0], v1 = acc[ai][bj][m][1];
; #pragma unroll
;                     for (int e = 0; e < 4; ++e) { const float a = fmaxf(v0[e], 0.f), b = fmaxf(v1[e], 0.f); v0[e] = a * a * rr; v1[e] = b * b * rr; }
;                     u32x4 w; w.x = cvt_pk_bf16(v0[0], v0[1]); w.y = cvt_pk_bf16(v0[2], v0[3]); w.z = cvt_pk_bf16(v1[0], v1[1]); w.w = cvt_pk_bf16(v1[2], v1[3]);
;                     *(u32x4*)(rowp + (size_t)bj * (2 * 256 * 64)) = w; } }
	v_pk_mul_f32 v[80:81], v[80:81], v[80:81]
	v_pk_mul_f32 v[82:83], v[82:83], v[82:83]
	v_pk_mul_f32 v[84:85], v[84:85], v[246:247] op_sel:[0,1] op_sel_hi:[1,1]
	v_pk_mul_f32 v[86:87], v[86:87], v[246:247] op_sel:[0,1] op_sel_hi:[1,1]
	v_pk_mul_f32 v[80:81], v[80:81], v[246:247] op_sel:[0,1] op_sel_hi:[1,1]
	v_pk_mul_f32 v[82:83], v[82:83], v[246:247] op_sel:[0,1] op_sel_hi:[1,1]
	v_cvt_pk_bf16_f32 v83, v82, v83
	v_cvt_pk_bf16_f32 v82, v80, v81
	v_cvt_pk_bf16_f32 v80, v84, v85
	v_cvt_pk_bf16_f32 v81, v86, v87
	v_add_co_u32_e32 v84, vcc, s49, v96
	s_nop 1
	v_addc_co_u32_e32 v85, vcc, 0, v97, vcc
	global_store_dwordx4 v[84:85], v[80:83], off
	v_max_f32_e32 v76, 0, v76
	v_max_f32_e32 v77, 0, v77
	v_max_f32_e32 v78, 0, v78
	v_max_f32_e32 v79, 0, v79
	v_max_f32_e32 v72, 0, v72
	v_max_f32_e32 v73, 0, v73
	v_max_f32_e32 v74, 0, v74
	v_max_f32_e32 v75, 0, v75
	v_pk_mul_f32 v[76:77], v[76:77], v[76:77]
	v_pk_mul_f32 v[78:79], v[78:79], v[78:79]
	v_pk_mul_f32 v[72:73], v[72:73], v[72:73]
	v_pk_mul_f32 v[74:75], v[74:75], v[74:75]
	v_pk_mul_f32 v[76:77], v[76:77], v[248:249] op_sel_hi:[1,0]
	v_pk_mul_f32 v[78:79], v[78:79], v[248:249] op_sel_hi:[1,0]
	v_pk_mul_f32 v[72:73], v[72:73], v[248:249] op_sel_hi:[1,0]
	v_pk_mul_f32 v[74:75], v[74:75], v[248:249] op_sel_hi:[1,0]
	v_cvt_pk_bf16_f32 v75, v74, v75
	v_cvt_pk_bf16_f32 v74, v72, v73
	v_cvt_pk_bf16_f32 v72, v76, v77
	v_cvt_pk_bf16_f32 v73, v78, v79
	v_lshl_add_u64 v[80:81], s[8:9], 0, v[150:151]
	v_lshl_add_u64 v[80:81], v[80:81], 0, s[6:7]
	v_lshl_add_u64 v[80:81], v[80:81], 0, v[140:141]
	global_store_dwordx4 v[80:81], v[72:75], off
	v_max_f32_e32 v68, 0, v68
	v_max_f32_e32 v69, 0, v69
	v_max_f32_e32 v70, 0, v70
	v_max_f32_e32 v71, 0, v71
	v_max_f32_e32 v64, 0, v64
	v_max_f32_e32 v65, 0, v65
	v_max_f32_e32 v66, 0, v66
	v_max_f32_e32 v67, 0, v67
	v_pk_mul_f32 v[68:69], v[68:69], v[68:69]
	v_pk_mul_f32 v[70:71], v[70:71], v[70:71]
	v_pk_mul_f32 v[64:65], v[64:65], v[64:65]
	v_pk_mul_f32 v[66:67], v[66:67], v[66:67]
	v_pk_mul_f32 v[68:69], v[68:69], v[248:249] op_sel_hi:[1,0]
	v_pk_mul_f32 v[70:71], v[70:71], v[248:249] op_sel_hi:[1,0]
	v_pk_mul_f32 v[64:65], v[64:65], v[248:249] op_sel_hi:[1,0]
	v_pk_mul_f32 v[66:67], v[66:67], v[248:249] op_sel_hi:[1,0]
	v_cvt_pk_bf16_f32 v67, v66, v67
	v_cvt_pk_bf16_f32 v66, v64, v65
	v_cvt_pk_bf16_f32 v64, v68, v69
	v_cvt_pk_bf16_f32 v65, v70, v71
	v_add_co_u32_e32 v68, vcc, s49, v80
	s_nop 1
	v_addc_co_u32_e32 v69, vcc, 0, v81, vcc
	global_store_dwordx4 v[68:69], v[64:67], off
	v_max_f32_e32 v60, 0, v60
	v_max_f32_e32 v61, 0, v61
	v_max_f32_e32 v62, 0, v62
	v_max_f32_e32 v63, 0, v63
	v_max_f32_e32 v56, 0, v56
	v_max_f32_e32 v57, 0, v57
	v_max_f32_e32 v58, 0, v58
	v_max_f32_e32 v59, 0, v59
	v_pk_mul_f32 v[60:61], v[60:61], v[60:61]
	v_pk_mul_f32 v[62:63], v[62:63], v[62:63]
	v_pk_mul_f32 v[56:57], v[56:57], v[56:57]
	v_pk_mul_f32 v[58:59], v[58:59], v[58:59]
	v_pk_mul_f32 v[60:61], v[60:61], v[248:249] op_sel:[0,1] op_sel_hi:[1,1]
	v_pk_mul_f32 v[62:63], v[62:63], v[248:249] op_sel:[0,1] op_sel_hi:[1,1]
	v_pk_mul_f32 v[56:57], v[56:57], v[248:249] op_sel:[0,1] op_sel_hi:[1,1]
	v_pk_mul_f32 v[58:59], v[58:59], v[248:249] op_sel:[0,1] op_sel_hi:[1,1]
	v_cvt_pk_bf16_f32 v59, v58, v59
	v_cvt_pk_bf16_f32 v58, v56, v57
	v_cvt_pk_bf16_f32 v56, v60, v61
	v_cvt_pk_bf16_f32 v57, v62, v63
	v_lshl_add_u64 v[64:65], s[8:9], 0, v[152:153]
	v_lshl_add_u64 v[64:65], v[64:65], 0, s[6:7]
	v_lshl_add_u64 v[64:65], v[64:65], 0, v[140:141]
	global_store_dwordx4 v[64:65], v[56:59], off
	v_max_f32_e32 v52, 0, v52
	v_max_f32_e32 v53, 0, v53
	v_max_f32_e32 v54, 0, v54
	v_max_f32_e32 v55, 0, v55
	v_max_f32_e32 v48, 0, v48
	v_max_f32_e32 v49, 0, v49
	v_max_f32_e32 v50, 0, v50
	v_max_f32_e32 v51, 0, v51
	v_pk_mul_f32 v[52:53], v[52:53], v[52:53]
	v_pk_mul_f32 v[54:55], v[54:55], v[54:55]
	v_pk_mul_f32 v[48:49], v[48:49], v[48:49]
	v_pk_mul_f32 v[50:51], v[50:51], v[50:51]
	v_pk_mul_f32 v[52:53], v[52:53], v[248:249] op_sel:[0,1] op_sel_hi:[1,1]
	v_pk_mul_f32 v[54:55], v[54:55], v[248:249] op_sel:[0,1] op_sel_hi:[1,1]
	v_pk_mul_f32 v[48:49], v[48:49], v[248:249] op_sel:[0,1] op_sel_hi:[1,1]
	v_pk_mul_f32 v[50:51], v[50:51], v[248:249] op_sel:[0,1] op_sel_hi:[1,1]
	v_cvt_pk_bf16_f32 v51, v50, v51
	v_cvt_pk_bf16_f32 v50, v48, v49
	v_cvt_pk_bf16_f32 v48, v52, v53
	v_cvt_pk_bf16_f32 v49, v54, v55
	v_add_co_u32_e32 v52, vcc, s49, v64
	s_nop 1
	v_addc_co_u32_e32 v53, vcc, 0, v65, vcc
	global_store_dwordx4 v[52:53], v[48:51], off
	v_max_f32_e32 v44, 0, v44
	v_max_f32_e32 v45, 0, v45
	v_max_f32_e32 v46, 0, v46
	v_max_f32_e32 v47, 0, v47
	v_max_f32_e32 v40, 0, v40
	v_max_f32_e32 v41, 0, v41
	v_max_f32_e32 v42, 0, v42
	v_max_f32_e32 v43, 0, v43
	v_pk_mul_f32 v[44:45], v[44:45], v[44:45]
	v_pk_mul_f32 v[46:47], v[46:47], v[46:47]
	v_pk_mul_f32 v[40:41], v[40:41], v[40:41]
	v_pk_mul_f32 v[42:43], v[42:43], v[42:43]
	v_pk_mul_f32 v[44:45], v[44:45], v[250:251] op_sel_hi:[1,0]
	v_pk_mul_f32 v[46:47], v[46:47], v[250:251] op_sel_hi:[1,0]
	v_pk_mul_f32 v[40:41], v[40:41], v[250:251] op_sel_hi:[1,0]
	v_pk_mul_f32 v[42:43], v[42:43], v[250:251] op_sel_hi:[1,0]
; __device__ __forceinline__ unsigned cvt_pk_bf16(float lo, float hi) { unsigned r; asm volatile("v_cvt_pk_bf16_f32 %0, %1, %2" : "=v"(r) : "v"(lo), "v"(hi)); return r; }
;     __device__ __forceinline__ void operator()(const f32x4 (&acc)[2][2][4][2], const Unit& u, int wr, int wc, int fr, int fq) const {
;     ...
;             for (int m = 0; m < 4; ++m) { const int row = row0 + ai * HALF + m * 16; const float rr = r2[ai][m];
;                 bf16_t* rowp = O + ((size_t)u.pm * (ldc / 64) * 256 + (size_t)(row - u.pm * BM)) * 64 + (size_t)(col0 >> 6) * (256 * 64) + (col0 & 63);
; #pragma unroll
;                 for (int bj = 0; bj < 2; ++bj) { f32x4 v0 = acc[ai][bj][m][0], v1 = acc[ai][bj][m][1];
; #pragma unroll
;                     for (int e = 0; e < 4; ++e) { const float a = fmaxf(v0[e], 0.f), b = fmaxf(v1[e], 0.f); v0[e] = a * a * rr; v1[e] = b * b * rr; }
;                     u32x4 w; w.x = cvt_pk_bf16(v0[0], v0[1]); w.y = cvt_pk_bf16(v0[2], v0[3]); w.z = cvt_pk_bf16(v1[0], v1[1]); w.w = cvt_pk_bf16(v1[2], v1[3]);
;                     *(u32x4*)(rowp + (size_t)bj * (2 * 256 * 64)) = w; } }
; template <class Epi, class Sched, bool ALIGN_EPI = false, bool SP2 = false, bool ABLK = false>
; __device__ __forceinline__ void gemm_phase(PG8_LAS unsigned char* lds, const Gemm g, const Sched& S, const Epi& E) {
;     ...
;         if constexpr (!Epi::AFTER_DRAIN) { E(acc, cur, wr, wc, fr, fq); S.done(cur); }
;         if (!has_next) break;
	v_cvt_pk_bf16_f32 v43, v42, v43
	v_cvt_pk_bf16_f32 v42, v40, v41
	v_cvt_pk_bf16_f32 v40, v44, v45
	v_cvt_pk_bf16_f32 v41, v46, v47
	v_lshl_add_u64 v[48:49], s[8:9], 0, v[154:155]
	v_lshl_add_u64 v[48:49], v[48:49], 0, s[6:7]
	v_lshl_add_u64 v[48:49], v[48:49], 0, v[140:141]
	global_store_dwordx4 v[48:49], v[40:43], off
	v_max_f32_e32 v36, 0, v36
	v_max_f32_e32 v37, 0, v37
	v_max_f32_e32 v38, 0, v38
	v_max_f32_e32 v39, 0, v39
	v_max_f32_e32 v32, 0, v32
	v_max_f32_e32 v33, 0, v33
	v_max_f32_e32 v34, 0, v34
	v_max_f32_e32 v35, 0, v35
	v_pk_mul_f32 v[36:37], v[36:37], v[36:37]
	v_pk_mul_f32 v[38:39], v[38:39], v[38:39]
	v_pk_mul_f32 v[32:33], v[32:33], v[32:33]
	v_pk_mul_f32 v[34:35], v[34:35], v[34:35]
	v_pk_mul_f32 v[36:37], v[36:37], v[250:251] op_sel_hi:[1,0]
	v_pk_mul_f32 v[38:39], v[38:39], v[250:251] op_sel_hi:[1,0]
	v_pk_mul_f32 v[32:33], v[32:33], v[250:251] op_sel_hi:[1,0]
	v_pk_mul_f32 v[34:35], v[34:35], v[250:251] op_sel_hi:[1,0]
	v_cvt_pk_bf16_f32 v35, v34, v35
	v_cvt_pk_bf16_f32 v34, v32, v33
	v_cvt_pk_bf16_f32 v32, v36, v37
	v_cvt_pk_bf16_f32 v33, v38, v39
	v_add_co_u32_e32 v36, vcc, s49, v48
	s_nop 1
	v_addc_co_u32_e32 v37, vcc, 0, v49, vcc
	global_store_dwordx4 v[36:37], v[32:35], off
	v_max_f32_e32 v28, 0, v28
	v_max_f32_e32 v29, 0, v29
	v_max_f32_e32 v30, 0, v30
	v_max_f32_e32 v31, 0, v31
	v_max_f32_e32 v24, 0, v24
	v_max_f32_e32 v25, 0, v25
	v_max_f32_e32 v26, 0, v26
	v_max_f32_e32 v27, 0, v27
	v_pk_mul_f32 v[28:29], v[28:29], v[28:29]
	v_pk_mul_f32 v[30:31], v[30:31], v[30:31]
	v_pk_mul_f32 v[24:25], v[24:25], v[24:25]
	v_pk_mul_f32 v[26:27], v[26:27], v[26:27]
	v_pk_mul_f32 v[28:29], v[28:29], v[250:251] op_sel:[0,1] op_sel_hi:[1,1]
	v_pk_mul_f32 v[30:31], v[30:31], v[250:251] op_sel:[0,1] op_sel_hi:[1,1]
	v_pk_mul_f32 v[24:25], v[24:25], v[250:251] op_sel:[0,1] op_sel_hi:[1,1]
	v_pk_mul_f32 v[26:27], v[26:27], v[250:251] op_sel:[0,1] op_sel_hi:[1,1]
	v_cvt_pk_bf16_f32 v27, v26, v27
	v_cvt_pk_bf16_f32 v26, v24, v25
	v_cvt_pk_bf16_f32 v24, v28, v29
	v_cvt_pk_bf16_f32 v25, v30, v31
	v_lshl_add_u64 v[32:33], s[8:9], 0, v[156:157]
	v_lshl_add_u64 v[32:33], v[32:33], 0, s[6:7]
	v_lshl_add_u64 v[32:33], v[32:33], 0, v[140:141]
	global_store_dwordx4 v[32:33], v[24:27], off
	v_max_f32_e32 v20, 0, v20
	v_max_f32_e32 v21, 0, v21
	v_max_f32_e32 v22, 0, v22
	v_max_f32_e32 v23, 0, v23
	v_max_f32_e32 v16, 0, v16
	v_max_f32_e32 v17, 0, v17
	v_max_f32_e32 v18, 0, v18
	v_max_f32_e32 v19, 0, v19
	v_pk_mul_f32 v[20:21], v[20:21], v[20:21]
	v_pk_mul_f32 v[22:23], v[22:23], v[22:23]
	v_pk_mul_f32 v[16:17], v[16:17], v[16:17]
	v_pk_mul_f32 v[18:19], v[18:19], v[18:19]
	v_pk_mul_f32 v[20:21], v[20:21], v[250:251] op_sel:[0,1] op_sel_hi:[1,1]
	v_pk_mul_f32 v[22:23], v[22:23], v[250:251] op_sel:[0,1] op_sel_hi:[1,1]
	v_pk_mul_f32 v[16:17], v[16:17], v[250:251] op_sel:[0,1] op_sel_hi:[1,1]
	v_pk_mul_f32 v[18:19], v[18:19], v[250:251] op_sel:[0,1] op_sel_hi:[1,1]
	v_cvt_pk_bf16_f32 v19, v18, v19
	v_cvt_pk_bf16_f32 v18, v16, v17
	v_cvt_pk_bf16_f32 v16, v20, v21
	v_cvt_pk_bf16_f32 v17, v22, v23
	v_add_co_u32_e32 v20, vcc, s49, v32
	s_nop 1
	v_addc_co_u32_e32 v21, vcc, 0, v33, vcc
	global_store_dwordx4 v[20:21], v[16:19], off
	v_max_f32_e32 v12, 0, v12
	v_max_f32_e32 v13, 0, v13
	v_max_f32_e32 v14, 0, v14
	v_max_f32_e32 v15, 0, v15
	v_max_f32_e32 v8, 0, v8
	v_max_f32_e32 v9, 0, v9
	v_max_f32_e32 v10, 0, v10
	v_max_f32_e32 v11, 0, v11
	v_pk_mul_f32 v[12:13], v[12:13], v[12:13]
	v_pk_mul_f32 v[14:15], v[14:15], v[14:15]
	v_pk_mul_f32 v[8:9], v[8:9], v[8:9]
	v_pk_mul_f32 v[10:11], v[10:11], v[10:11]
	v_pk_mul_f32 v[12:13], v[12:13], v[252:253] op_sel_hi:[1,0]
	v_pk_mul_f32 v[14:15], v[14:15], v[252:253] op_sel_hi:[1,0]
	v_pk_mul_f32 v[8:9], v[8:9], v[252:253] op_sel_hi:[1,0]
	v_pk_mul_f32 v[10:11], v[10:11], v[252:253] op_sel_hi:[1,0]
	v_cvt_pk_bf16_f32 v11, v10, v11
	v_cvt_pk_bf16_f32 v10, v8, v9
	v_cvt_pk_bf16_f32 v8, v12, v13
	v_cvt_pk_bf16_f32 v9, v14, v15
	v_lshl_add_u64 v[16:17], s[8:9], 0, v[158:159]
	v_lshl_add_u64 v[16:17], v[16:17], 0, s[6:7]
	v_lshl_add_u64 v[16:17], v[16:17], 0, v[140:141]
	global_store_dwordx4 v[16:17], v[8:11], off
	v_max_f32_e32 v4, 0, v4
	v_max_f32_e32 v5, 0, v5
	v_max_f32_e32 v6, 0, v6
	v_max_f32_e32 v7, 0, v7
	v_max_f32_e32 v0, 0, v0
	v_max_f32_e32 v1, 0, v1
	v_max_f32_e32 v2, 0, v2
	v_max_f32_e32 v3, 0, v3
	v_pk_mul_f32 v[4:5], v[4:5], v[4:5]
	v_pk_mul_f32 v[6:7], v[6:7], v[6:7]
	v_pk_mul_f32 v[0:1], v[0:1], v[0:1]
	v_pk_mul_f32 v[2:3], v[2:3], v[2:3]
	v_pk_mul_f32 v[4:5], v[4:5], v[252:253] op_sel_hi:[1,0]
	v_pk_mul_f32 v[6:7], v[6:7], v[252:253] op_sel_hi:[1,0]
	v_pk_mul_f32 v[0:1], v[0:1], v[252:253] op_sel_hi:[1,0]
	v_pk_mul_f32 v[2:3], v[2:3], v[252:253] op_sel_hi:[1,0]
	v_cvt_pk_bf16_f32 v3, v2, v3
	v_cvt_pk_bf16_f32 v2, v0, v1
	v_cvt_pk_bf16_f32 v0, v4, v5
	v_cvt_pk_bf16_f32 v1, v6, v7
	v_add_co_u32_e32 v4, vcc, 0x10000, v16
	s_nop 1
	v_addc_co_u32_e32 v5, vcc, 0, v17, vcc
	s_andn2_b64 vcc, exec, s[26:27]
	s_mov_b64 s[6:7], -1
	global_store_dwordx4 v[4:5], v[0:3], off
	s_cbranch_vccnz .LBB0_530
	s_andn2_b64 vcc, exec, s[14:15]
	s_cbranch_vccnz .LBB0_529
	s_barrier
	s_branch .LBB0_529
